# k17 + S2: per-row decay weights computed from 15 loads issued together (was 8 dependent load-wait steps per unit)
# baseline (speedup 1.0000x reference)
.LBB0_1377:
	s_or_b64 exec, exec, s[2:3]
	s_or_b32 s2, s0, 0x7f
	s_ashr_i32 s3, s2, 31
	s_lshl_b32 s39, s63, 2
	s_lshl_b64 s[2:3], s[2:3], 7
	s_add_u32 s40, s18, s2
	s_addc_u32 s41, s19, s3
	s_ashr_i32 s2, s0, 6
	v_add_u32_e32 v22, s0, v150
	v_mov_b32_e32 v5, v121
	v_or_b32_e32 v18, s39, v151
	s_ashr_i32 s3, s2, 31
	v_ashrrev_i32_e32 v23, 31, v22
	v_lshl_add_u64 v[128:129], v[2:3], 0, v[4:5]
	v_lshlrev_b32_e32 v25, 2, v18
	s_lshl_b64 s[2:3], s[2:3], 7
	v_lshlrev_b64 v[26:27], 7, v[22:23]
	v_add_co_u32_e32 v2, vcc, 0x2000, v128
	s_add_u32 s42, s48, s2
	v_or_b32_e32 v26, v26, v25
	v_addc_co_u32_e32 v3, vcc, 0, v129, vcc
	s_addc_u32 s43, s49, s3
	v_lshl_add_u64 v[28:29], s[18:19], 0, v[26:27]
	global_load_dwordx4 v[74:77], v[2:3], off
	global_load_dword v18, v25, s[40:41]
	global_load_dword v21, v[28:29], off
	global_load_dword v20, v25, s[42:43]
	v_lshl_add_u64 v[26:27], s[16:17], 0, v[26:27]
	v_add_co_u32_e32 v2, vcc, s58, v128
	global_load_dwordx4 v[82:85], v[128:129], off
	s_nop 0
	v_addc_co_u32_e32 v3, vcc, 0, v129, vcc
	global_load_dwordx4 v[58:61], v[2:3], off
	s_mov_b32 s1, 0xa000
	v_readlane_b32 s80, v254, 34
	v_readlane_b32 s92, v254, 46
	v_readlane_b32 s93, v254, 47
	v_lshlrev_b32_e32 v120, 2, v24
	v_readlane_b32 s94, v254, 48
	v_readlane_b32 s95, v254, 49
	s_mov_b64 s[68:69], s[92:93]
	s_mov_b64 s[70:71], s[94:95]
	s_waitcnt vmcnt(6)
	v_lshlrev_b32_e32 v86, 16, v66
	v_and_b32_e32 v87, 0xffff0000, v66
	v_lshlrev_b32_e32 v66, 16, v67
	v_and_b32_e32 v67, 0xffff0000, v67
	v_lshlrev_b32_e32 v94, 16, v71
	v_and_b32_e32 v95, 0xffff0000, v71
	v_lshlrev_b32_e32 v92, 16, v70
	v_and_b32_e32 v93, 0xffff0000, v70
	v_lshlrev_b32_e32 v100, 16, v79
	v_and_b32_e32 v101, 0xffff0000, v79
	v_lshlrev_b32_e32 v98, 16, v78
	v_and_b32_e32 v99, 0xffff0000, v78
	v_lshlrev_b32_e32 v108, 16, v73
	v_and_b32_e32 v109, 0xffff0000, v73
	v_lshlrev_b32_e32 v102, 16, v80
	v_and_b32_e32 v103, 0xffff0000, v80
	v_lshlrev_b32_e32 v106, 16, v81
	v_and_b32_e32 v107, 0xffff0000, v81
	v_lshl_or_b32 v136, s63, 7, v149
	v_readlane_b32 s81, v254, 35
	v_readlane_b32 s82, v254, 36
	v_readlane_b32 s83, v254, 37
	v_readlane_b32 s84, v254, 38
	v_readlane_b32 s85, v254, 39
	v_readlane_b32 s86, v254, 40
	v_readlane_b32 s87, v254, 41
	v_readlane_b32 s88, v254, 42
	v_readlane_b32 s89, v254, 43
	v_readlane_b32 s90, v254, 44
	v_readlane_b32 s91, v254, 45
	s_waitcnt vmcnt(5)
	v_lshlrev_b32_e32 v104, 16, v75
	v_and_b32_e32 v105, 0xffff0000, v75
	v_lshlrev_b32_e32 v132, 16, v77
	global_load_dword v164, v[26:27], off
	global_load_dword v165, v[28:29], off offset:128
	global_load_dword v166, v[26:27], off offset:128
	global_load_dword v167, v[28:29], off offset:256
	global_load_dword v168, v[26:27], off offset:256
	global_load_dword v169, v[28:29], off offset:384
	global_load_dword v170, v[26:27], off offset:384
	global_load_dword v171, v[28:29], off offset:512
	global_load_dword v172, v[26:27], off offset:512
	global_load_dword v173, v[28:29], off offset:640
	global_load_dword v174, v[26:27], off offset:640
	global_load_dword v175, v[28:29], off offset:768
	global_load_dword v176, v[26:27], off offset:768
	global_load_dword v177, v[28:29], off offset:896
	global_load_dword v178, v[26:27], off offset:896
	s_waitcnt vmcnt(17)
	v_cndmask_b32_e64 v19, 0, v20, s[6:7]
	v_pk_add_f32 v[20:21], v[18:19], v[20:21]
	v_and_b32_e32 v133, 0xffff0000, v77
	v_sub_f32_e32 v180, v20, v21
	s_waitcnt vmcnt(0)
	v_add_f32_e32 v181, v19, v165
	v_sub_f32_e32 v181, v20, v181
	v_add_f32_e32 v182, v19, v167
	v_sub_f32_e32 v182, v20, v182
	v_add_f32_e32 v183, v19, v169
	v_sub_f32_e32 v183, v20, v183
	v_add_f32_e32 v184, v19, v171
	v_sub_f32_e32 v184, v20, v184
	v_add_f32_e32 v185, v19, v173
	v_sub_f32_e32 v185, v20, v185
	v_add_f32_e32 v186, v19, v175
	v_sub_f32_e32 v186, v20, v186
	v_add_f32_e32 v187, v19, v177
	v_sub_f32_e32 v187, v20, v187
	v_exp_f32_e32 v180, v180
	v_exp_f32_e32 v181, v181
	v_exp_f32_e32 v182, v182
	v_exp_f32_e32 v183, v183
	v_exp_f32_e32 v184, v184
	v_exp_f32_e32 v185, v185
	v_exp_f32_e32 v186, v186
	v_exp_f32_e32 v187, v187
	v_mul_f32_e32 v137, v164, v180
	v_mul_f32_e32 v138, v166, v181
	v_mul_f32_e32 v139, v168, v182
	v_mul_f32_e32 v140, v170, v183
	v_mul_f32_e32 v141, v172, v184
	v_mul_f32_e32 v142, v174, v185
	v_mul_f32_e32 v143, v176, v186
	v_mov_b32_e32 v20, v187
	v_mov_b32_e32 v18, v178
	v_add_co_u32_e32 v2, vcc, s57, v128
	v_lshl_add_u64 v[22:23], s[68:69], 0, v[120:121]
	s_nop 0
	v_addc_co_u32_e32 v3, vcc, 0, v129, vcc
	global_load_dwordx4 v[38:41], v[2:3], off
	v_add_co_u32_e32 v2, vcc, s59, v128
	v_lshl_add_u64 v[24:25], v[22:23], 0, s[22:23]
	s_nop 0
	v_addc_co_u32_e32 v3, vcc, 0, v129, vcc
	global_load_dwordx4 v[14:17], v[2:3], off
	v_add_co_u32_e32 v2, vcc, s1, v128
	v_lshlrev_b32_e32 v88, 16, v83
	s_nop 0
	v_addc_co_u32_e32 v3, vcc, 0, v129, vcc
	global_load_dwordx4 v[10:13], v[2:3], off
	v_add_co_u32_e32 v2, vcc, s60, v128
	v_and_b32_e32 v89, 0xffff0000, v83
	s_nop 0
	v_addc_co_u32_e32 v3, vcc, 0, v129, vcc
	global_load_dwordx4 v[6:9], v[2:3], off
	v_add_co_u32_e32 v2, vcc, s56, v128
	v_lshlrev_b32_e32 v90, 16, v84
	s_nop 0
	v_addc_co_u32_e32 v3, vcc, 0, v129, vcc
	v_add_co_u32_e32 v26, vcc, s58, v22
	global_load_dwordx4 v[2:5], v[2:3], off
	s_nop 0
	v_addc_co_u32_e32 v27, vcc, 0, v23, vcc
	v_add_co_u32_e32 v30, vcc, s59, v22
	v_and_b32_e32 v91, 0xffff0000, v84
	s_nop 0
	v_addc_co_u32_e32 v31, vcc, 0, v23, vcc
	v_lshlrev_b32_e32 v96, 16, v85
	v_and_b32_e32 v97, 0xffff0000, v85
	v_lshlrev_b32_e32 v130, 16, v61
	v_and_b32_e32 v131, 0xffff0000, v61
	s_waitcnt vmcnt(5)
	v_mul_f32_e32 v144, v18, v20
	global_load_dwordx4 v[18:21], v120, s[68:69] offset:16
	global_load_dwordx4 v[42:45], v120, s[68:69]
	global_load_dwordx4 v[50:53], v[26:27], off
	s_nop 0
	global_load_dwordx4 v[26:29], v[24:25], off offset:16
	v_lshl_add_u64 v[24:25], v[22:23], 0, s[26:27]
	global_load_dwordx4 v[54:57], v[30:31], off
	s_nop 0
	global_load_dwordx4 v[30:33], v[24:25], off offset:16
	v_lshl_add_u64 v[24:25], v[22:23], 0, s[30:31]
	v_add_co_u32_e32 v22, vcc, s60, v22
	s_waitcnt vmcnt(10)
	v_lshlrev_b32_e32 v114, 16, v39
	v_addc_co_u32_e32 v23, vcc, 0, v23, vcc
	global_load_dwordx4 v[46:49], v[22:23], off
	s_nop 0
	global_load_dwordx4 v[22:25], v[24:25], off offset:16
	s_nop 0
	global_load_dwordx4 v[34:37], v120, s[70:71] offset:16
	global_load_dwordx4 v[62:65], v120, s[70:71]
	v_and_b32_e32 v115, 0xffff0000, v39
	v_lshlrev_b32_e32 v110, 16, v38
	v_and_b32_e32 v111, 0xffff0000, v38
	v_lshlrev_b32_e32 v116, 16, v41
	v_and_b32_e32 v117, 0xffff0000, v41
	s_waitcnt vmcnt(13)
	v_lshlrev_b32_e32 v112, 16, v15
	v_and_b32_e32 v113, 0xffff0000, v15
	s_waitcnt vmcnt(12)
	v_lshlrev_b32_e32 v134, 16, v11
	v_and_b32_e32 v135, 0xffff0000, v11
	v_lshlrev_b32_e32 v120, 1, v136
	s_waitcnt vmcnt(0)
	v_pk_fma_f32 v[66:67], v[44:45], v[66:67], v[64:65]
	v_pk_fma_f32 v[86:87], v[42:43], v[86:87], v[62:63]
	v_pk_fma_f32 v[66:67], v[52:53], v[94:95], v[66:67]
	v_pk_fma_f32 v[70:71], v[50:51], v[92:93], v[86:87]
	v_pk_fma_f32 v[66:67], v[56:57], v[100:101], v[66:67]
	v_pk_fma_f32 v[70:71], v[54:55], v[98:99], v[70:71]
	v_lshlrev_b32_e32 v86, 16, v82
	v_and_b32_e32 v87, 0xffff0000, v82
	v_pk_fma_f32 v[66:67], v[48:49], v[88:89], v[66:67]
	v_pk_fma_f32 v[70:71], v[46:47], v[86:87], v[70:71]
	v_pk_mul_f32 v[78:79], v[66:67], s[36:37] op_sel_hi:[1,0]
	v_pk_mul_f32 v[82:83], v[70:71], s[36:37] op_sel_hi:[1,0]
	v_exp_f32_e32 v78, v78
	v_exp_f32_e32 v79, v79
	v_exp_f32_e32 v82, v82
	v_exp_f32_e32 v83, v83
	v_pk_add_f32 v[78:79], v[78:79], 1.0 op_sel_hi:[1,0]
	s_nop 0
	v_rcp_f32_e32 v78, v78
	v_pk_add_f32 v[82:83], v[82:83], 1.0 op_sel_hi:[1,0]
	v_rcp_f32_e32 v79, v79
	v_rcp_f32_e32 v82, v82
	v_rcp_f32_e32 v83, v83
	v_pk_mul_f32 v[66:67], v[66:67], v[78:79]
	v_lshlrev_b32_e32 v78, 16, v68
	v_and_b32_e32 v79, 0xffff0000, v68
	v_lshlrev_b32_e32 v68, 16, v69
	v_and_b32_e32 v69, 0xffff0000, v69
	v_pk_mul_f32 v[70:71], v[70:71], v[82:83]
	v_pk_fma_f32 v[68:69], v[20:21], v[68:69], v[36:37]
	v_pk_fma_f32 v[78:79], v[18:19], v[78:79], v[34:35]
	v_lshlrev_b32_e32 v82, 16, v72
	v_and_b32_e32 v83, 0xffff0000, v72
	v_pk_fma_f32 v[68:69], v[28:29], v[108:109], v[68:69]
	v_pk_fma_f32 v[72:73], v[26:27], v[82:83], v[78:79]
	v_pk_fma_f32 v[68:69], v[32:33], v[106:107], v[68:69]
	v_pk_fma_f32 v[72:73], v[30:31], v[102:103], v[72:73]
	v_pk_fma_f32 v[68:69], v[24:25], v[96:97], v[68:69]
	v_pk_fma_f32 v[72:73], v[22:23], v[90:91], v[72:73]
	v_pk_mul_f32 v[78:79], v[68:69], s[36:37] op_sel_hi:[1,0]
	v_pk_mul_f32 v[80:81], v[72:73], s[36:37] op_sel_hi:[1,0]
	v_exp_f32_e32 v78, v78
	v_exp_f32_e32 v80, v80
	v_exp_f32_e32 v81, v81
	v_exp_f32_e32 v79, v79
	v_pk_fma_f32 v[82:83], v[18:19], v[82:83], v[34:35]
	v_pk_add_f32 v[80:81], v[80:81], 1.0 op_sel_hi:[1,0]
	v_pk_add_f32 v[78:79], v[78:79], 1.0 op_sel_hi:[1,0]
	v_rcp_f32_e32 v80, v80
	v_rcp_f32_e32 v81, v81
	v_rcp_f32_e32 v78, v78
	v_rcp_f32_e32 v79, v79
	v_pk_fma_f32 v[82:83], v[26:27], v[102:103], v[82:83]
	v_pk_mul_f32 v[72:73], v[72:73], v[80:81]
	v_pk_fma_f32 v[80:81], v[42:43], v[92:93], v[62:63]
	v_pk_mul_f32 v[68:69], v[68:69], v[78:79]
	v_pk_fma_f32 v[78:79], v[44:45], v[94:95], v[64:65]
	v_pk_fma_f32 v[80:81], v[50:51], v[98:99], v[80:81]
	v_pk_fma_f32 v[78:79], v[52:53], v[100:101], v[78:79]
	v_pk_fma_f32 v[80:81], v[54:55], v[86:87], v[80:81]
	v_pk_fma_f32 v[78:79], v[56:57], v[88:89], v[78:79]
	v_lshlrev_b32_e32 v92, 16, v74
	v_and_b32_e32 v93, 0xffff0000, v74
	v_pk_fma_f32 v[80:81], v[46:47], v[92:93], v[80:81]
	v_pk_fma_f32 v[74:75], v[48:49], v[104:105], v[78:79]
	v_pk_mul_f32 v[84:85], v[80:81], s[36:37] op_sel_hi:[1,0]
	v_pk_mul_f32 v[78:79], v[74:75], s[36:37] op_sel_hi:[1,0]
	v_exp_f32_e32 v84, v84
	v_exp_f32_e32 v85, v85
	v_exp_f32_e32 v78, v78
	v_exp_f32_e32 v79, v79
	v_pk_fma_f32 v[82:83], v[30:31], v[90:91], v[82:83]
	v_pk_add_f32 v[84:85], v[84:85], 1.0 op_sel_hi:[1,0]
	v_lshlrev_b32_e32 v94, 16, v76
	v_pk_add_f32 v[78:79], v[78:79], 1.0 op_sel_hi:[1,0]
	v_rcp_f32_e32 v84, v84
	v_rcp_f32_e32 v85, v85
	v_rcp_f32_e32 v78, v78
	v_rcp_f32_e32 v79, v79
	v_and_b32_e32 v95, 0xffff0000, v76
	v_pk_fma_f32 v[82:83], v[22:23], v[94:95], v[82:83]
	v_pk_fma_f32 v[102:103], v[18:19], v[102:103], v[34:35]
	v_pk_mul_f32 v[74:75], v[74:75], v[78:79]
	v_pk_mul_f32 v[78:79], v[80:81], v[84:85]
	v_pk_fma_f32 v[80:81], v[20:21], v[108:109], v[36:37]
	v_pk_mul_f32 v[84:85], v[82:83], s[36:37] op_sel_hi:[1,0]
	v_pk_fma_f32 v[80:81], v[28:29], v[106:107], v[80:81]
	v_exp_f32_e32 v84, v84
	v_pk_fma_f32 v[80:81], v[32:33], v[96:97], v[80:81]
	v_exp_f32_e32 v85, v85
	v_pk_fma_f32 v[76:77], v[24:25], v[132:133], v[80:81]
	v_pk_fma_f32 v[102:103], v[26:27], v[90:91], v[102:103]
	v_pk_mul_f32 v[80:81], v[76:77], s[36:37] op_sel_hi:[1,0]
	v_pk_add_f32 v[84:85], v[84:85], 1.0 op_sel_hi:[1,0]
	v_exp_f32_e32 v80, v80
	v_exp_f32_e32 v81, v81
	v_rcp_f32_e32 v84, v84
	v_rcp_f32_e32 v85, v85
	v_pk_fma_f32 v[90:91], v[18:19], v[90:91], v[34:35]
	v_pk_add_f32 v[80:81], v[80:81], 1.0 op_sel_hi:[1,0]
	v_pk_fma_f32 v[90:91], v[26:27], v[94:95], v[90:91]
	v_rcp_f32_e32 v80, v80
	v_rcp_f32_e32 v81, v81
	s_nop 0
	v_pk_mul_f32 v[76:77], v[76:77], v[80:81]
	v_pk_mul_f32 v[80:81], v[82:83], v[84:85]
	v_pk_fma_f32 v[82:83], v[44:45], v[100:101], v[64:65]
	v_pk_fma_f32 v[84:85], v[42:43], v[98:99], v[62:63]
	v_pk_fma_f32 v[82:83], v[52:53], v[88:89], v[82:83]
	v_pk_fma_f32 v[84:85], v[50:51], v[86:87], v[84:85]
	v_pk_fma_f32 v[82:83], v[56:57], v[104:105], v[82:83]
	v_pk_fma_f32 v[84:85], v[54:55], v[92:93], v[84:85]
	v_lshlrev_b32_e32 v98, 16, v58
	v_and_b32_e32 v99, 0xffff0000, v58
	v_lshlrev_b32_e32 v100, 16, v59
	v_and_b32_e32 v101, 0xffff0000, v59
	v_pk_fma_f32 v[84:85], v[46:47], v[98:99], v[84:85]
	v_pk_fma_f32 v[58:59], v[48:49], v[100:101], v[82:83]
	v_pk_mul_f32 v[108:109], v[84:85], s[36:37] op_sel_hi:[1,0]
	v_pk_mul_f32 v[82:83], v[58:59], s[36:37] op_sel_hi:[1,0]
	v_exp_f32_e32 v108, v108
	v_exp_f32_e32 v109, v109
	v_exp_f32_e32 v82, v82
	v_exp_f32_e32 v83, v83
	v_pk_fma_f32 v[88:89], v[44:45], v[88:89], v[64:65]
	v_pk_add_f32 v[108:109], v[108:109], 1.0 op_sel_hi:[1,0]
	v_pk_fma_f32 v[88:89], v[52:53], v[104:105], v[88:89]
	v_pk_add_f32 v[82:83], v[82:83], 1.0 op_sel_hi:[1,0]
	v_rcp_f32_e32 v108, v108
	v_rcp_f32_e32 v109, v109
	v_rcp_f32_e32 v82, v82
	v_rcp_f32_e32 v83, v83
	v_pk_fma_f32 v[86:87], v[42:43], v[86:87], v[62:63]
	v_pk_fma_f32 v[88:89], v[56:57], v[100:101], v[88:89]
	v_pk_fma_f32 v[86:87], v[50:51], v[92:93], v[86:87]
	v_pk_mul_f32 v[58:59], v[58:59], v[82:83]
	v_pk_mul_f32 v[82:83], v[84:85], v[108:109]
	v_pk_fma_f32 v[84:85], v[20:21], v[106:107], v[36:37]
	v_pk_fma_f32 v[106:107], v[30:31], v[94:95], v[102:103]
	v_pk_fma_f32 v[84:85], v[28:29], v[96:97], v[84:85]
	v_lshlrev_b32_e32 v102, 16, v60
	v_pk_fma_f32 v[84:85], v[32:33], v[132:133], v[84:85]
	v_and_b32_e32 v103, 0xffff0000, v60
	v_pk_fma_f32 v[106:107], v[22:23], v[102:103], v[106:107]
	v_pk_fma_f32 v[60:61], v[24:25], v[130:131], v[84:85]
	v_pk_mul_f32 v[108:109], v[106:107], s[36:37] op_sel_hi:[1,0]
	v_pk_mul_f32 v[84:85], v[60:61], s[36:37] op_sel_hi:[1,0]
	v_exp_f32_e32 v108, v108
	v_exp_f32_e32 v109, v109
	v_exp_f32_e32 v84, v84
	v_exp_f32_e32 v85, v85
	v_pk_fma_f32 v[38:39], v[48:49], v[114:115], v[88:89]
	v_pk_add_f32 v[108:109], v[108:109], 1.0 op_sel_hi:[1,0]
	v_pk_fma_f32 v[86:87], v[54:55], v[98:99], v[86:87]
	v_pk_add_f32 v[84:85], v[84:85], 1.0 op_sel_hi:[1,0]
	v_rcp_f32_e32 v108, v108
	v_rcp_f32_e32 v109, v109
	v_rcp_f32_e32 v84, v84
	v_rcp_f32_e32 v85, v85
	v_pk_mul_f32 v[88:89], v[38:39], s[36:37] op_sel_hi:[1,0]
	v_pk_fma_f32 v[86:87], v[46:47], v[110:111], v[86:87]
	v_exp_f32_e32 v88, v88
	v_exp_f32_e32 v89, v89
	v_pk_mul_f32 v[60:61], v[60:61], v[84:85]
	v_pk_mul_f32 v[84:85], v[106:107], v[108:109]
	v_pk_mul_f32 v[106:107], v[86:87], s[36:37] op_sel_hi:[1,0]
	v_pk_add_f32 v[88:89], v[88:89], 1.0 op_sel_hi:[1,0]
	v_exp_f32_e32 v106, v106
	v_exp_f32_e32 v107, v107
	v_rcp_f32_e32 v88, v88
	v_rcp_f32_e32 v89, v89
	v_pk_fma_f32 v[90:91], v[30:31], v[102:103], v[90:91]
	v_pk_add_f32 v[106:107], v[106:107], 1.0 op_sel_hi:[1,0]
	v_lshlrev_b32_e32 v108, 16, v14
	v_rcp_f32_e32 v106, v106
	v_rcp_f32_e32 v107, v107
	v_pk_mul_f32 v[38:39], v[38:39], v[88:89]
	v_pk_fma_f32 v[88:89], v[20:21], v[96:97], v[36:37]
	v_and_b32_e32 v109, 0xffff0000, v14
	v_pk_fma_f32 v[88:89], v[28:29], v[132:133], v[88:89]
	v_pk_mul_f32 v[86:87], v[86:87], v[106:107]
	v_pk_fma_f32 v[88:89], v[32:33], v[130:131], v[88:89]
	v_lshlrev_b32_e32 v106, 16, v40
	v_and_b32_e32 v107, 0xffff0000, v40
	v_pk_fma_f32 v[90:91], v[22:23], v[106:107], v[90:91]
	v_pk_fma_f32 v[40:41], v[24:25], v[116:117], v[88:89]
	v_pk_mul_f32 v[96:97], v[90:91], s[36:37] op_sel_hi:[1,0]
	v_pk_mul_f32 v[88:89], v[40:41], s[36:37] op_sel_hi:[1,0]
	v_exp_f32_e32 v96, v96
	v_exp_f32_e32 v97, v97
	v_exp_f32_e32 v88, v88
	v_exp_f32_e32 v89, v89
	v_pk_fma_f32 v[94:95], v[18:19], v[94:95], v[34:35]
	v_pk_add_f32 v[96:97], v[96:97], 1.0 op_sel_hi:[1,0]
	v_pk_fma_f32 v[94:95], v[26:27], v[102:103], v[94:95]
	v_pk_add_f32 v[88:89], v[88:89], 1.0 op_sel_hi:[1,0]
	v_rcp_f32_e32 v96, v96
	v_rcp_f32_e32 v97, v97
	v_rcp_f32_e32 v88, v88
	v_rcp_f32_e32 v89, v89
	v_pk_fma_f32 v[94:95], v[30:31], v[106:107], v[94:95]
	v_pk_fma_f32 v[102:103], v[18:19], v[102:103], v[34:35]
	v_pk_mul_f32 v[40:41], v[40:41], v[88:89]
	v_pk_mul_f32 v[88:89], v[90:91], v[96:97]
	v_pk_fma_f32 v[90:91], v[42:43], v[92:93], v[62:63]
	v_pk_fma_f32 v[92:93], v[44:45], v[104:105], v[64:65]
	v_pk_fma_f32 v[90:91], v[50:51], v[98:99], v[90:91]
	v_pk_fma_f32 v[92:93], v[52:53], v[100:101], v[92:93]
	v_pk_fma_f32 v[90:91], v[54:55], v[110:111], v[90:91]
	v_pk_fma_f32 v[92:93], v[56:57], v[114:115], v[92:93]
	v_pk_fma_f32 v[100:101], v[44:45], v[100:101], v[64:65]
	v_pk_fma_f32 v[14:15], v[48:49], v[112:113], v[92:93]
	v_pk_fma_f32 v[92:93], v[46:47], v[108:109], v[90:91]
	v_pk_mul_f32 v[90:91], v[14:15], s[36:37] op_sel_hi:[1,0]
	v_pk_mul_f32 v[96:97], v[92:93], s[36:37] op_sel_hi:[1,0]
	v_exp_f32_e32 v90, v90
	v_exp_f32_e32 v91, v91
	v_exp_f32_e32 v96, v96
	v_exp_f32_e32 v97, v97
	v_pk_fma_f32 v[98:99], v[42:43], v[98:99], v[62:63]
	v_pk_add_f32 v[90:91], v[90:91], 1.0 op_sel_hi:[1,0]
	v_pk_fma_f32 v[100:101], v[52:53], v[114:115], v[100:101]
	v_rcp_f32_e32 v90, v90
	v_rcp_f32_e32 v91, v91
	v_pk_add_f32 v[96:97], v[96:97], 1.0 op_sel_hi:[1,0]
	v_pk_fma_f32 v[98:99], v[50:51], v[110:111], v[98:99]
	v_rcp_f32_e32 v96, v96
	v_rcp_f32_e32 v97, v97
	v_pk_mul_f32 v[90:91], v[14:15], v[90:91]
	v_pk_fma_f32 v[14:15], v[20:21], v[132:133], v[36:37]
	v_pk_fma_f32 v[100:101], v[56:57], v[112:113], v[100:101]
	v_pk_fma_f32 v[14:15], v[28:29], v[130:131], v[14:15]
	v_pk_mul_f32 v[92:93], v[92:93], v[96:97]
	v_pk_fma_f32 v[96:97], v[32:33], v[116:117], v[14:15]
	v_lshlrev_b32_e32 v14, 16, v16
	v_and_b32_e32 v15, 0xffff0000, v16
	v_lshlrev_b32_e32 v16, 16, v17
	v_and_b32_e32 v17, 0xffff0000, v17
	v_pk_fma_f32 v[104:105], v[22:23], v[14:15], v[94:95]
	v_pk_fma_f32 v[94:95], v[24:25], v[16:17], v[96:97]
	v_pk_mul_f32 v[132:133], v[104:105], s[36:37] op_sel_hi:[1,0]
	v_pk_mul_f32 v[96:97], v[94:95], s[36:37] op_sel_hi:[1,0]
	v_exp_f32_e32 v132, v132
	v_exp_f32_e32 v133, v133
	v_exp_f32_e32 v96, v96
	v_exp_f32_e32 v97, v97
	v_pk_fma_f32 v[98:99], v[54:55], v[108:109], v[98:99]
	v_pk_add_f32 v[132:133], v[132:133], 1.0 op_sel_hi:[1,0]
	v_pk_fma_f32 v[102:103], v[26:27], v[106:107], v[102:103]
	v_pk_add_f32 v[96:97], v[96:97], 1.0 op_sel_hi:[1,0]
	v_rcp_f32_e32 v132, v132
	v_rcp_f32_e32 v133, v133
	v_rcp_f32_e32 v96, v96
	v_rcp_f32_e32 v97, v97
	v_pk_fma_f32 v[102:103], v[30:31], v[14:15], v[102:103]
	v_pk_fma_f32 v[114:115], v[44:45], v[114:115], v[64:65]
	v_pk_fma_f32 v[110:111], v[42:43], v[110:111], v[62:63]
	v_pk_mul_f32 v[94:95], v[94:95], v[96:97]
	v_pk_mul_f32 v[96:97], v[104:105], v[132:133]
	v_lshlrev_b32_e32 v132, 16, v10
	v_and_b32_e32 v133, 0xffff0000, v10
	v_pk_fma_f32 v[10:11], v[48:49], v[134:135], v[100:101]
	v_pk_fma_f32 v[100:101], v[46:47], v[132:133], v[98:99]
	v_pk_mul_f32 v[98:99], v[10:11], s[36:37] op_sel_hi:[1,0]
	v_pk_mul_f32 v[104:105], v[100:101], s[36:37] op_sel_hi:[1,0]
	v_exp_f32_e32 v98, v98
	v_exp_f32_e32 v99, v99
	v_exp_f32_e32 v104, v104
	v_exp_f32_e32 v105, v105
	v_pk_fma_f32 v[114:115], v[52:53], v[112:113], v[114:115]
	v_pk_add_f32 v[98:99], v[98:99], 1.0 op_sel_hi:[1,0]
	v_pk_fma_f32 v[42:43], v[42:43], v[108:109], v[62:63]
	v_rcp_f32_e32 v98, v98
	v_rcp_f32_e32 v99, v99
	v_pk_add_f32 v[104:105], v[104:105], 1.0 op_sel_hi:[1,0]
	v_pk_fma_f32 v[44:45], v[44:45], v[112:113], v[64:65]
	v_rcp_f32_e32 v104, v104
	v_rcp_f32_e32 v105, v105
	v_pk_mul_f32 v[98:99], v[10:11], v[98:99]
	v_pk_fma_f32 v[10:11], v[20:21], v[130:131], v[36:37]
	v_pk_fma_f32 v[114:115], v[56:57], v[134:135], v[114:115]
	v_pk_fma_f32 v[10:11], v[28:29], v[116:117], v[10:11]
	v_pk_mul_f32 v[100:101], v[100:101], v[104:105]
	v_pk_fma_f32 v[104:105], v[32:33], v[16:17], v[10:11]
	v_lshlrev_b32_e32 v10, 16, v12
	v_and_b32_e32 v11, 0xffff0000, v12
	v_lshlrev_b32_e32 v12, 16, v13
	v_and_b32_e32 v13, 0xffff0000, v13
	v_pk_fma_f32 v[130:131], v[22:23], v[10:11], v[102:103]
	v_pk_fma_f32 v[102:103], v[24:25], v[12:13], v[104:105]
	v_pk_mul_f32 v[146:147], v[130:131], s[36:37] op_sel_hi:[1,0]
	v_pk_mul_f32 v[104:105], v[102:103], s[36:37] op_sel_hi:[1,0]
	v_exp_f32_e32 v146, v146
	v_exp_f32_e32 v147, v147
	v_exp_f32_e32 v104, v104
	v_exp_f32_e32 v105, v105
	v_pk_fma_f32 v[44:45], v[52:53], v[134:135], v[44:45]
	v_pk_add_f32 v[146:147], v[146:147], 1.0 op_sel_hi:[1,0]
	v_pk_fma_f32 v[42:43], v[50:51], v[132:133], v[42:43]
	v_pk_add_f32 v[104:105], v[104:105], 1.0 op_sel_hi:[1,0]
	v_rcp_f32_e32 v146, v146
	v_rcp_f32_e32 v147, v147
	v_rcp_f32_e32 v104, v104
	v_rcp_f32_e32 v105, v105
	v_pk_fma_f32 v[110:111], v[50:51], v[108:109], v[110:111]
	v_pk_fma_f32 v[116:117], v[20:21], v[116:117], v[36:37]
	v_pk_fma_f32 v[110:111], v[54:55], v[132:133], v[110:111]
	v_pk_mul_f32 v[102:103], v[102:103], v[104:105]
	v_pk_mul_f32 v[104:105], v[130:131], v[146:147]
	v_lshlrev_b32_e32 v130, 16, v6
	v_and_b32_e32 v131, 0xffff0000, v6
	v_lshlrev_b32_e32 v6, 16, v7
	v_and_b32_e32 v7, 0xffff0000, v7
	v_pk_fma_f32 v[114:115], v[48:49], v[6:7], v[114:115]
	v_pk_fma_f32 v[6:7], v[56:57], v[6:7], v[44:45]
	v_pk_fma_f32 v[42:43], v[54:55], v[130:131], v[42:43]
	v_lshlrev_b32_e32 v44, 16, v2
	v_and_b32_e32 v45, 0xffff0000, v2
	v_lshlrev_b32_e32 v2, 16, v3
	v_and_b32_e32 v3, 0xffff0000, v3
	v_pk_fma_f32 v[2:3], v[48:49], v[2:3], v[6:7]
	v_pk_fma_f32 v[6:7], v[46:47], v[44:45], v[42:43]
	v_pk_fma_f32 v[146:147], v[46:47], v[130:131], v[110:111]
	v_pk_mul_f32 v[42:43], v[2:3], s[36:37] op_sel_hi:[1,0]
	v_pk_mul_f32 v[44:45], v[6:7], s[36:37] op_sel_hi:[1,0]
	v_pk_mul_f32 v[110:111], v[114:115], s[36:37] op_sel_hi:[1,0]
	v_pk_mul_f32 v[160:161], v[146:147], s[36:37] op_sel_hi:[1,0]
	v_exp_f32_e32 v44, v44
	v_exp_f32_e32 v45, v45
	v_exp_f32_e32 v42, v42
	v_exp_f32_e32 v43, v43
	v_exp_f32_e32 v160, v160
	v_exp_f32_e32 v161, v161
	v_exp_f32_e32 v110, v110
	v_exp_f32_e32 v111, v111
	v_pk_add_f32 v[42:43], v[42:43], 1.0 op_sel_hi:[1,0]
	v_pk_add_f32 v[44:45], v[44:45], 1.0 op_sel_hi:[1,0]
	v_pk_add_f32 v[160:161], v[160:161], 1.0 op_sel_hi:[1,0]
	v_pk_add_f32 v[110:111], v[110:111], 1.0 op_sel_hi:[1,0]
	v_rcp_f32_e32 v44, v44
	v_rcp_f32_e32 v45, v45
	v_rcp_f32_e32 v42, v42
	v_rcp_f32_e32 v43, v43
	v_rcp_f32_e32 v160, v160
	v_rcp_f32_e32 v161, v161
	v_rcp_f32_e32 v110, v110
	v_rcp_f32_e32 v111, v111
	v_pk_fma_f32 v[106:107], v[18:19], v[106:107], v[34:35]
	v_pk_fma_f32 v[116:117], v[28:29], v[16:17], v[116:117]
	v_pk_fma_f32 v[106:107], v[26:27], v[14:15], v[106:107]
	v_pk_mul_f32 v[42:43], v[2:3], v[42:43]
	v_pk_mul_f32 v[44:45], v[6:7], v[44:45]
	v_pk_fma_f32 v[2:3], v[20:21], v[16:17], v[36:37]
	v_pk_fma_f32 v[6:7], v[18:19], v[14:15], v[34:35]
	v_pk_mul_f32 v[110:111], v[114:115], v[110:111]
	v_pk_mul_f32 v[114:115], v[146:147], v[160:161]
	v_pk_fma_f32 v[116:117], v[32:33], v[12:13], v[116:117]
	v_pk_fma_f32 v[106:107], v[30:31], v[10:11], v[106:107]
	v_lshlrev_b32_e32 v146, 16, v8
	v_and_b32_e32 v147, 0xffff0000, v8
	v_lshlrev_b32_e32 v8, 16, v9
	v_and_b32_e32 v9, 0xffff0000, v9
	v_pk_fma_f32 v[6:7], v[26:27], v[10:11], v[6:7]
	v_pk_fma_f32 v[2:3], v[28:29], v[12:13], v[2:3]
	v_pk_fma_f32 v[160:161], v[22:23], v[146:147], v[106:107]
	v_pk_fma_f32 v[106:107], v[24:25], v[8:9], v[116:117]
	v_pk_fma_f32 v[2:3], v[32:33], v[8:9], v[2:3]
	v_pk_fma_f32 v[6:7], v[30:31], v[146:147], v[6:7]
	v_lshlrev_b32_e32 v8, 16, v4
	v_and_b32_e32 v9, 0xffff0000, v4
	v_lshlrev_b32_e32 v4, 16, v5
	v_and_b32_e32 v5, 0xffff0000, v5
	v_pk_fma_f32 v[6:7], v[22:23], v[8:9], v[6:7]
	v_pk_fma_f32 v[2:3], v[24:25], v[4:5], v[2:3]
	v_pk_mul_f32 v[8:9], v[6:7], s[36:37] op_sel_hi:[1,0]
	v_pk_mul_f32 v[4:5], v[2:3], s[36:37] op_sel_hi:[1,0]
	v_exp_f32_e32 v8, v8
	v_exp_f32_e32 v9, v9
	v_exp_f32_e32 v4, v4
	v_exp_f32_e32 v5, v5
	v_mul_f32_e32 v10, v137, v69
	v_pk_add_f32 v[8:9], v[8:9], 1.0 op_sel_hi:[1,0]
	v_mul_f32_e32 v11, v138, v79
	v_pk_add_f32 v[4:5], v[4:5], 1.0 op_sel_hi:[1,0]
	v_rcp_f32_e32 v8, v8
	v_rcp_f32_e32 v9, v9
	v_rcp_f32_e32 v4, v4
	v_rcp_f32_e32 v5, v5
	v_mul_f32_e32 v12, v138, v75
	v_pk_mul_f32 v[36:37], v[6:7], v[8:9]
	v_mul_f32_e32 v6, v137, v70
	v_mul_f32_e32 v7, v137, v71
	v_pk_mul_f32 v[46:47], v[2:3], v[4:5]
	v_cvt_pk_bf16_f32 v2, v70, v71
	v_cvt_pk_bf16_f32 v3, v66, v67
	v_cvt_pk_bf16_f32 v4, v72, v73
	v_cvt_pk_bf16_f32 v5, v68, v69
	v_cvt_pk_bf16_f32 v6, v6, v7
	v_mul_f32_e32 v7, v137, v66
	v_mul_f32_e32 v8, v137, v67
	v_cvt_pk_bf16_f32 v7, v7, v8
	v_mul_f32_e32 v8, v137, v72
	v_mul_f32_e32 v9, v137, v73
	v_cvt_pk_bf16_f32 v8, v8, v9
	v_mul_f32_e32 v9, v137, v68
	v_cvt_pk_bf16_f32 v9, v9, v10
	v_mul_f32_e32 v10, v138, v78
	ds_write_b128 v156, v[6:9]
	v_cvt_pk_bf16_f32 v6, v78, v79
	v_cvt_pk_bf16_f32 v7, v74, v75
	v_cvt_pk_bf16_f32 v8, v80, v81
	v_cvt_pk_bf16_f32 v9, v76, v77
	v_cvt_pk_bf16_f32 v10, v10, v11
	v_mul_f32_e32 v11, v138, v74
	v_cvt_pk_bf16_f32 v11, v11, v12
	v_mul_f32_e32 v12, v138, v80
	v_mul_f32_e32 v13, v138, v81
	v_cvt_pk_bf16_f32 v12, v12, v13
	v_mul_f32_e32 v13, v138, v76
	v_mul_f32_e32 v14, v138, v77
	v_cvt_pk_bf16_f32 v13, v13, v14
	v_mul_f32_e32 v14, v139, v82
	v_mul_f32_e32 v15, v139, v83
	ds_write_b128 v156, v[10:13] offset:64
	v_cvt_pk_bf16_f32 v10, v82, v83
	v_cvt_pk_bf16_f32 v11, v58, v59
	v_cvt_pk_bf16_f32 v12, v84, v85
	v_cvt_pk_bf16_f32 v13, v60, v61
	v_cvt_pk_bf16_f32 v14, v14, v15
	v_mul_f32_e32 v15, v139, v58
	v_mul_f32_e32 v16, v139, v59
	v_cvt_pk_bf16_f32 v15, v15, v16
	v_mul_f32_e32 v16, v139, v84
	v_mul_f32_e32 v17, v139, v85
	v_cvt_pk_bf16_f32 v16, v16, v17
	v_mul_f32_e32 v17, v139, v60
	v_mul_f32_e32 v18, v139, v61
	v_cvt_pk_bf16_f32 v17, v17, v18
	v_mul_f32_e32 v18, v140, v86
	v_mul_f32_e32 v19, v140, v87
	ds_write_b128 v156, v[14:17] offset:128
	v_cvt_pk_bf16_f32 v14, v86, v87
	v_cvt_pk_bf16_f32 v15, v38, v39
	v_cvt_pk_bf16_f32 v16, v88, v89
	v_cvt_pk_bf16_f32 v17, v40, v41
	v_cvt_pk_bf16_f32 v18, v18, v19
	v_mul_f32_e32 v19, v140, v38
	v_mul_f32_e32 v20, v140, v39
	v_cvt_pk_bf16_f32 v19, v19, v20
	v_mul_f32_e32 v20, v140, v88
	v_mul_f32_e32 v21, v140, v89
	v_pk_mul_f32 v[116:117], v[106:107], s[36:37] op_sel_hi:[1,0]
	v_pk_mul_f32 v[162:163], v[160:161], s[36:37] op_sel_hi:[1,0]
	v_cvt_pk_bf16_f32 v20, v20, v21
	v_mul_f32_e32 v21, v140, v40
	v_mul_f32_e32 v22, v140, v41
	v_exp_f32_e32 v162, v162
	v_exp_f32_e32 v163, v163
	v_exp_f32_e32 v116, v116
	v_exp_f32_e32 v117, v117
	v_cvt_pk_bf16_f32 v21, v21, v22
	v_mul_f32_e32 v22, v141, v92
	v_mul_f32_e32 v23, v141, v93
	ds_write_b128 v156, v[18:21] offset:192
	v_cvt_pk_bf16_f32 v18, v92, v93
	v_cvt_pk_bf16_f32 v19, v90, v91
	v_cvt_pk_bf16_f32 v20, v96, v97
	v_cvt_pk_bf16_f32 v21, v94, v95
	v_cvt_pk_bf16_f32 v22, v22, v23
	v_mul_f32_e32 v23, v141, v90
	v_mul_f32_e32 v24, v141, v91
	v_cvt_pk_bf16_f32 v23, v23, v24
	v_mul_f32_e32 v24, v141, v96
	v_mul_f32_e32 v25, v141, v97
	v_cvt_pk_bf16_f32 v24, v24, v25
	v_mul_f32_e32 v25, v141, v94
	v_mul_f32_e32 v26, v141, v95
	v_pk_add_f32 v[116:117], v[116:117], 1.0 op_sel_hi:[1,0]
	v_pk_add_f32 v[162:163], v[162:163], 1.0 op_sel_hi:[1,0]
	v_cvt_pk_bf16_f32 v25, v25, v26
	v_mul_f32_e32 v26, v142, v100
	v_mul_f32_e32 v27, v142, v101
	v_rcp_f32_e32 v162, v162
	v_rcp_f32_e32 v163, v163
	v_rcp_f32_e32 v116, v116
	v_rcp_f32_e32 v117, v117
	ds_write_b128 v156, v[22:25] offset:256
	v_cvt_pk_bf16_f32 v22, v100, v101
	v_cvt_pk_bf16_f32 v23, v98, v99
	v_cvt_pk_bf16_f32 v24, v104, v105
	v_cvt_pk_bf16_f32 v25, v102, v103
	v_cvt_pk_bf16_f32 v26, v26, v27
	v_mul_f32_e32 v27, v142, v98
	v_mul_f32_e32 v28, v142, v99
	v_cvt_pk_bf16_f32 v27, v27, v28
	v_mul_f32_e32 v28, v142, v104
	v_mul_f32_e32 v29, v142, v105
	v_cvt_pk_bf16_f32 v28, v28, v29
	v_mul_f32_e32 v29, v142, v102
	v_mul_f32_e32 v30, v142, v103
	v_cvt_pk_bf16_f32 v29, v29, v30
	v_mul_f32_e32 v30, v143, v114
	v_mul_f32_e32 v31, v143, v115
	v_pk_mul_f32 v[106:107], v[106:107], v[116:117]
	v_pk_mul_f32 v[116:117], v[160:161], v[162:163]
	ds_write_b128 v156, v[26:29] offset:320
	v_cvt_pk_bf16_f32 v26, v114, v115
	v_cvt_pk_bf16_f32 v27, v110, v111
	v_cvt_pk_bf16_f32 v28, v116, v117
	v_cvt_pk_bf16_f32 v29, v106, v107
	v_cvt_pk_bf16_f32 v30, v30, v31
	v_mul_f32_e32 v31, v143, v110
	v_mul_f32_e32 v32, v143, v111
	v_cvt_pk_bf16_f32 v31, v31, v32
	v_mul_f32_e32 v32, v143, v116
	v_mul_f32_e32 v33, v143, v117
	v_cvt_pk_bf16_f32 v32, v32, v33
	v_mul_f32_e32 v33, v143, v106
	v_mul_f32_e32 v34, v143, v107
	v_cvt_pk_bf16_f32 v33, v33, v34
	v_mul_f32_e32 v34, v144, v44
	v_mul_f32_e32 v35, v144, v45
	ds_write_b128 v156, v[30:33] offset:384
	v_cvt_pk_bf16_f32 v30, v44, v45
	v_cvt_pk_bf16_f32 v31, v42, v43
	v_cvt_pk_bf16_f32 v32, v36, v37
	v_cvt_pk_bf16_f32 v33, v46, v47
	v_cvt_pk_bf16_f32 v34, v34, v35
	v_mul_f32_e32 v35, v144, v42
	v_mul_f32_e32 v36, v144, v36
	v_mul_f32_e32 v37, v144, v37
	v_mul_f32_e32 v38, v144, v43
	v_cvt_pk_bf16_f32 v35, v35, v38
	v_cvt_pk_bf16_f32 v36, v36, v37
	v_mul_f32_e32 v37, v144, v46
	v_mul_f32_e32 v38, v144, v47
	v_cvt_pk_bf16_f32 v37, v37, v38
	ds_write_b128 v156, v[34:37] offset:448
	v_or_b32_e32 v36, s65, v152
	v_lshl_add_u64 v[34:35], s[46:47], 0, v[120:121]
	v_lshlrev_b32_e32 v36, 13, v36
	s_and_saveexec_b64 s[0:1], s[8:9]
	s_xor_b64 s[2:3], exec, s[0:1]
	s_cbranch_execz .LBB0_1379
	v_mov_b32_e32 v37, v121
	v_lshl_add_u64 v[38:39], v[34:35], 0, v[36:37]
	v_add_co_u32_e32 v38, vcc, 0xffffa000, v38
	s_nop 1
	v_addc_co_u32_e32 v39, vcc, -1, v39, vcc
	global_load_dwordx4 v[86:89], v[38:39], off
	s_or_saveexec_b64 s[2:3], s[2:3]
	v_lshl_add_u64 v[38:39], s[44:45], 0, v[120:121]
	s_xor_b64 exec, exec, s[2:3]
	s_cbranch_execz .LBB0_1382
	s_branch .LBB0_1380

.LBB0_1625:
	s_ashr_i32 s29, s28, 31
	s_lshl_b64 s[0:1], s[28:29], 20
	s_add_u32 s30, s33, s0
	s_addc_u32 s31, s42, s1
	s_and_b64 s[0:1], s[6:7], exec
	s_cselect_b32 s11, s31, s39
	s_cselect_b32 s29, s30, s38
	s_ashr_i32 s27, s26, 31
	s_lshl_b64 s[0:1], s[26:27], 20
	s_add_u32 s34, s43, s0
	s_addc_u32 s35, s44, s1
	s_and_b64 s[0:1], s[6:7], exec
	s_cselect_b32 s27, s35, s3
	s_cselect_b32 s56, s34, s2
	s_add_u32 s38, s38, 0x80080
	s_addc_u32 s39, s39, 0
	s_add_u32 s57, s2, 0x100
	v_mov_b32_e32 v2, 0
	s_addc_u32 s58, s3, 0
	s_mov_b32 s59, -2
	s_waitcnt lgkmcnt(0)
	v_mov_b32_e32 v3, v2
	v_mov_b32_e32 v4, v2
	v_mov_b32_e32 v5, v2
	v_mov_b32_e32 v6, v2
	v_mov_b32_e32 v7, v2
	v_mov_b32_e32 v8, v2
	v_mov_b32_e32 v9, v2
	v_mov_b32_e32 v18, v2
	v_mov_b32_e32 v19, v2
	v_mov_b32_e32 v20, v2
	v_mov_b32_e32 v21, v2
	v_mov_b32_e32 v22, v2
	v_mov_b32_e32 v23, v2
	v_mov_b32_e32 v24, v2
	v_mov_b32_e32 v25, v2
	v_mov_b32_e32 v34, v2
	v_mov_b32_e32 v35, v2
	v_mov_b32_e32 v36, v2
	v_mov_b32_e32 v37, v2
	v_mov_b32_e32 v38, v2
	v_mov_b32_e32 v39, v2
	v_mov_b32_e32 v40, v2
	v_mov_b32_e32 v41, v2
	v_mov_b32_e32 v50, v2
	v_mov_b32_e32 v51, v2
	v_mov_b32_e32 v52, v2
	v_mov_b32_e32 v53, v2
	v_mov_b32_e32 v54, v2
	v_mov_b32_e32 v55, v2
	v_mov_b32_e32 v56, v2
	v_mov_b32_e32 v57, v2
	v_mov_b32_e32 v10, v2
	v_mov_b32_e32 v11, v2
	v_mov_b32_e32 v12, v2
	v_mov_b32_e32 v13, v2
	v_mov_b32_e32 v14, v2
	v_mov_b32_e32 v15, v2
	v_mov_b32_e32 v16, v2
	v_mov_b32_e32 v17, v2
	v_mov_b32_e32 v26, v2
	v_mov_b32_e32 v27, v2
	v_mov_b32_e32 v28, v2
	v_mov_b32_e32 v29, v2
	v_mov_b32_e32 v30, v2
	v_mov_b32_e32 v31, v2
	v_mov_b32_e32 v32, v2
	v_mov_b32_e32 v33, v2
	v_mov_b32_e32 v42, v2
	v_mov_b32_e32 v43, v2
	v_mov_b32_e32 v44, v2
	v_mov_b32_e32 v45, v2
	v_mov_b32_e32 v46, v2
	v_mov_b32_e32 v47, v2
	v_mov_b32_e32 v48, v2
	v_mov_b32_e32 v49, v2
	v_mov_b32_e32 v58, v2
	v_mov_b32_e32 v59, v2
	v_mov_b32_e32 v60, v2
	v_mov_b32_e32 v61, v2
	v_mov_b32_e32 v62, v2
	v_mov_b32_e32 v63, v2
	v_mov_b32_e32 v64, v2
	v_mov_b32_e32 v65, v2
	v_mov_b32_e32 v66, v2
	v_mov_b32_e32 v67, v2
	v_mov_b32_e32 v68, v2
	v_mov_b32_e32 v69, v2
	v_mov_b32_e32 v70, v2
	v_mov_b32_e32 v71, v2
	v_mov_b32_e32 v72, v2
	v_mov_b32_e32 v73, v2
	v_mov_b32_e32 v82, v2
	v_mov_b32_e32 v83, v2
	v_mov_b32_e32 v84, v2
	v_mov_b32_e32 v85, v2
	v_mov_b32_e32 v86, v2
	v_mov_b32_e32 v87, v2
	v_mov_b32_e32 v88, v2
	v_mov_b32_e32 v89, v2
	v_mov_b32_e32 v98, v2
	v_mov_b32_e32 v99, v2
	v_mov_b32_e32 v100, v2
	v_mov_b32_e32 v101, v2
	v_mov_b32_e32 v102, v2
	v_mov_b32_e32 v103, v2
	v_mov_b32_e32 v104, v2
	v_mov_b32_e32 v105, v2
	v_mov_b32_e32 v114, v2
	v_mov_b32_e32 v115, v2
	v_mov_b32_e32 v116, v2
	v_mov_b32_e32 v117, v2
	v_mov_b32_e32 v118, v2
	v_mov_b32_e32 v119, v2
	v_mov_b32_e32 v120, v2
	v_mov_b32_e32 v121, v2
	v_mov_b32_e32 v74, v2
	v_mov_b32_e32 v75, v2
	v_mov_b32_e32 v76, v2
	v_mov_b32_e32 v77, v2
	v_mov_b32_e32 v78, v2
	v_mov_b32_e32 v79, v2
	v_mov_b32_e32 v80, v2
	v_mov_b32_e32 v81, v2
	v_mov_b32_e32 v90, v2
	v_mov_b32_e32 v91, v2
	v_mov_b32_e32 v92, v2
	v_mov_b32_e32 v93, v2
	v_mov_b32_e32 v94, v2
	v_mov_b32_e32 v95, v2
	v_mov_b32_e32 v96, v2
	v_mov_b32_e32 v97, v2
	v_mov_b32_e32 v106, v2
	v_mov_b32_e32 v107, v2
	v_mov_b32_e32 v108, v2
	v_mov_b32_e32 v109, v2
	v_mov_b32_e32 v110, v2
	v_mov_b32_e32 v111, v2
	v_mov_b32_e32 v112, v2
	v_mov_b32_e32 v113, v2
	v_mov_b32_e32 v122, v2
	v_mov_b32_e32 v123, v2
	v_mov_b32_e32 v124, v2
	v_mov_b32_e32 v125, v2
	v_mov_b32_e32 v126, v2
	v_mov_b32_e32 v127, v2
	v_mov_b32_e32 v128, v2
	v_mov_b32_e32 v129, v2
	s_nop 0
	s_nop 0
	s_nop 0
	s_nop 0
	s_nop 0
	s_nop 0
	s_nop 0
	s_nop 0
	s_nop 0
	s_nop 0
	s_nop 0
	s_nop 0
	s_nop 0
	s_nop 0
